# P4 pre(): wave 0 (barrier protocol) issues its residual x loads after the protocol so no barrier step waits on the x burst
# speedup vs baseline: 1.0046x; 1.0046x over previous
.LBB0_927:
	s_or_b64 exec, exec, s[8:9]
	s_mov_b64 s[98:99], s[36:37]
	s_cmp_eq_u32 s39, 0
	s_cbranch_scc1 .Lp4x_skip_w0
	s_lshr_b32 s44, s39, 8
	s_lshl_b32 s52, s44, 6
	s_lshl_b32 s5, s4, 8
	s_add_i32 s5, s5, s52
	v_or_b32_e32 v4, s5, v3
	v_ashrrev_i32_e32 v5, 31, v4
	v_lshlrev_b64 v[4:5], 12, v[4:5]
	s_lshl_b32 s8, s16, 8
	s_bfe_u32 s3, s39, 0x20006
	v_lshl_add_u64 v[4:5], s[36:37], 0, v[4:5]
	s_ashr_i32 s9, s8, 31
	v_lshl_add_u64 v[4:5], s[8:9], 2, v[4:5]
	s_lshl_b32 s8, s3, 8
	s_mov_b32 s9, 0
	v_mov_b32_e32 v159, 0
	v_lshl_add_u64 v[4:5], v[4:5], 0, s[8:9]
	v_lshlrev_b32_e32 v6, 2, v191
	v_mov_b32_e32 v7, v159
	v_lshl_add_u64 v[116:117], v[4:5], 0, v[6:7]
	s_mov_b32 s5, 0x10000
	v_add_co_u32_e32 v44, vcc, s5, v116
	s_mov_b32 s5, 0x20000
	s_nop 0
	v_addc_co_u32_e32 v45, vcc, 0, v117, vcc
	s_mov_b64 s[12:13], 0x30000
	v_add_co_u32_e32 v52, vcc, s5, v116
	v_lshl_add_u64 v[36:37], v[116:117], 0, s[12:13]
	s_mov_b64 s[12:13], 0x10080
	v_addc_co_u32_e32 v53, vcc, 0, v117, vcc
	s_mov_b32 s5, 0x30000
	v_lshl_add_u64 v[70:71], v[116:117], 0, s[12:13]
	s_mov_b64 s[12:13], 0x20080
	s_mov_b64 s[10:11], 0x10000
	s_mov_b64 s[8:9], 0x20000
	v_add_co_u32_e32 v68, vcc, s5, v116
	v_lshl_add_u64 v[72:73], v[116:117], 0, s[12:13]
	s_mov_b64 s[12:13], 0x30080
	v_lshl_add_u64 v[20:21], v[116:117], 0, s[10:11]
	v_lshl_add_u64 v[46:47], v[116:117], 0, s[8:9]
	v_addc_co_u32_e32 v69, vcc, 0, v117, vcc
	v_lshl_add_u64 v[74:75], v[116:117], 0, s[12:13]
	s_mov_b64 s[12:13], 0x80000
	s_mov_b32 s5, 0x80000
	global_load_dwordx4 v[4:7], v[116:117], off offset:16
	global_load_dwordx4 v[8:11], v[116:117], off
	global_load_dwordx4 v[12:15], v[44:45], off
	global_load_dwordx4 v[16:19], v[20:21], off offset:16
	s_nop 0
	global_load_dwordx4 v[20:23], v[68:69], off
	global_load_dwordx4 v[24:27], v[36:37], off offset:16
	global_load_dwordx4 v[28:31], v[116:117], off offset:144
	global_load_dwordx4 v[32:35], v[116:117], off offset:128
	s_nop 0
	global_load_dwordx4 v[36:39], v[46:47], off offset:16
	global_load_dwordx4 v[40:43], v[44:45], off offset:128
	s_nop 0
	global_load_dwordx4 v[44:47], v[52:53], off
	global_load_dwordx4 v[48:51], v[52:53], off offset:128
	s_nop 0
	global_load_dwordx4 v[52:55], v[70:71], off offset:16
	global_load_dwordx4 v[56:59], v[68:69], off offset:128
	global_load_dwordx4 v[60:63], v[72:73], off offset:16
	global_load_dwordx4 v[64:67], v[74:75], off offset:16
	v_lshl_add_u64 v[72:73], v[116:117], 0, s[12:13]
	v_add_co_u32_e32 v88, vcc, s5, v116
	s_mov_b64 s[12:13], 0x90000
	s_nop 0
	v_addc_co_u32_e32 v89, vcc, 0, v117, vcc
	v_lshl_add_u64 v[84:85], v[116:117], 0, s[12:13]
	s_mov_b32 s5, 0x90000
	s_mov_b64 s[12:13], 0xa0000
	v_add_co_u32_e32 v96, vcc, s5, v116
	v_lshl_add_u64 v[80:81], v[116:117], 0, s[12:13]
	s_mov_b64 s[12:13], 0xb0000
	v_addc_co_u32_e32 v97, vcc, 0, v117, vcc
	s_mov_b32 s5, 0xa0000
	v_lshl_add_u64 v[108:109], v[116:117], 0, s[12:13]
	s_mov_b64 s[12:13], 0x80080
	v_add_co_u32_e32 v112, vcc, s5, v116
	v_lshl_add_u64 v[100:101], v[116:117], 0, s[12:13]
	s_mov_b64 s[12:13], 0x90080
	v_addc_co_u32_e32 v113, vcc, 0, v117, vcc
	s_mov_b32 s5, 0xb0000
	v_lshl_add_u64 v[104:105], v[116:117], 0, s[12:13]
	s_mov_b64 s[12:13], 0xa0080
	v_add_co_u32_e32 v120, vcc, s5, v116
	v_lshl_add_u64 v[124:125], v[116:117], 0, s[12:13]
	s_mov_b64 s[12:13], 0xb0080
	v_addc_co_u32_e32 v121, vcc, 0, v117, vcc
	v_lshl_add_u64 v[128:129], v[116:117], 0, s[12:13]
	global_load_dwordx4 v[68:71], v[88:89], off
	s_nop 0
	global_load_dwordx4 v[72:75], v[72:73], off offset:16
	s_nop 0
	global_load_dwordx4 v[76:79], v[112:113], off
	s_nop 0
	global_load_dwordx4 v[80:83], v[80:81], off offset:16
	s_nop 0
	global_load_dwordx4 v[84:87], v[84:85], off offset:16
	s_nop 0
	global_load_dwordx4 v[88:91], v[88:89], off offset:128
	s_nop 0
	global_load_dwordx4 v[92:95], v[96:97], off
	s_nop 0
	global_load_dwordx4 v[96:99], v[96:97], off offset:128
	s_nop 0
	global_load_dwordx4 v[100:103], v[100:101], off offset:16
	s_nop 0
	global_load_dwordx4 v[104:107], v[104:105], off offset:16
	s_nop 0
	global_load_dwordx4 v[108:111], v[108:109], off offset:16
	s_nop 0
	global_load_dwordx4 v[112:115], v[112:113], off offset:128
	s_nop 0
	global_load_dwordx4 v[116:119], v[120:121], off
	s_nop 0
	global_load_dwordx4 v[120:123], v[120:121], off offset:128
	s_nop 0
	global_load_dwordx4 v[124:127], v[124:125], off offset:16
	s_nop 0
	global_load_dwordx4 v[128:131], v[128:129], off offset:16
.Lp4x_skip_w0:
	s_lshr_b32 s5, s39, 6
	s_and_saveexec_b64 s[12:13], s[96:97]
	s_cbranch_execz .LBB0_962
	v_cvt_f32_u32_e32 v133, v134
	v_sub_u32_e32 v135, 0, v134
	v_add_u32_e32 v136, 1, v1
	v_rcp_iflag_f32_e32 v133, v133
	s_nop 0
	v_mul_f32_e32 v133, 0x4f7ffffe, v133
	v_cvt_u32_f32_e32 v133, v133
	v_mul_lo_u32 v135, v135, v133
	v_mul_hi_u32 v135, v133, v135
	v_add_u32_e32 v133, v133, v135
	v_mul_hi_u32 v133, v1, v133
	v_mul_lo_u32 v135, v133, v134
	v_sub_u32_e32 v1, v1, v135
	v_add_u32_e32 v137, 1, v133
	v_cmp_ge_u32_e32 vcc, v1, v134
	v_sub_u32_e32 v135, v1, v134
	s_nop 0
	v_cndmask_b32_e32 v133, v133, v137, vcc
	v_cndmask_b32_e32 v1, v1, v135, vcc
	v_add_u32_e32 v135, 1, v133
	v_cmp_ge_u32_e32 vcc, v1, v134
	s_nop 1
	v_cndmask_b32_e32 v1, v133, v135, vcc
	v_mad_u64_u32 v[134:135], s[14:15], v134, v1, v[134:135]
	v_cmp_ne_u32_e32 vcc, v136, v134
	s_and_saveexec_b64 s[14:15], vcc
	s_xor_b64 s[14:15], exec, s[14:15]
	s_cbranch_execz .LBB0_942
	v_readlane_b32 s17, v254, 2
	s_lshl_b32 s17, s17, 8
	s_waitcnt vmcnt(0) lgkmcnt(0)
	buffer_inv sc1
	s_waitcnt vmcnt(0)
	s_getpc_b64 s[18:19]
	s_add_u32 s18, s18, g_ctl@rel32@lo+25604
	s_addc_u32 s19, s19, g_ctl@rel32@hi+25612
	v_mov_b32_e32 v132, s17
	global_load_dword v132, v132, s[18:19] sc1
	s_add_u32 s20, s18, s17
	s_addc_u32 s21, s19, 0
	s_waitcnt vmcnt(0)
	v_cmp_eq_u32_e32 vcc, v132, v1
	s_and_saveexec_b64 s[18:19], vcc
	s_cbranch_execz .LBB0_941
	s_mov_b32 s17, 1
	s_mov_b64 s[22:23], 0
	v_mov_b32_e32 v132, 0
	s_branch .LBB0_932

.LBB0_962:
	s_or_b64 exec, exec, s[12:13]
	s_cmp_lg_u32 s39, 0
	s_cbranch_scc1 .Lp4x_done_w0
	s_lshr_b32 s44, s39, 8
	s_lshl_b32 s52, s44, 6
	s_lshl_b32 s5, s4, 8
	s_add_i32 s5, s5, s52
	v_or_b32_e32 v4, s5, v3
	v_ashrrev_i32_e32 v5, 31, v4
	v_lshlrev_b64 v[4:5], 12, v[4:5]
	s_lshl_b32 s8, s16, 8
	s_bfe_u32 s3, s39, 0x20006
	v_lshl_add_u64 v[4:5], s[98:99], 0, v[4:5]
	s_ashr_i32 s9, s8, 31
	v_lshl_add_u64 v[4:5], s[8:9], 2, v[4:5]
	s_lshl_b32 s8, s3, 8
	s_mov_b32 s9, 0
	v_mov_b32_e32 v159, 0
	v_lshl_add_u64 v[4:5], v[4:5], 0, s[8:9]
	v_lshlrev_b32_e32 v6, 2, v191
	v_mov_b32_e32 v7, v159
	v_lshl_add_u64 v[116:117], v[4:5], 0, v[6:7]
	s_mov_b32 s5, 0x10000
	v_add_co_u32_e32 v44, vcc, s5, v116
	s_mov_b32 s5, 0x20000
	s_nop 0
	v_addc_co_u32_e32 v45, vcc, 0, v117, vcc
	s_mov_b64 s[12:13], 0x30000
	v_add_co_u32_e32 v52, vcc, s5, v116
	v_lshl_add_u64 v[36:37], v[116:117], 0, s[12:13]
	s_mov_b64 s[12:13], 0x10080
	v_addc_co_u32_e32 v53, vcc, 0, v117, vcc
	s_mov_b32 s5, 0x30000
	v_lshl_add_u64 v[70:71], v[116:117], 0, s[12:13]
	s_mov_b64 s[12:13], 0x20080
	s_mov_b64 s[10:11], 0x10000
	s_mov_b64 s[8:9], 0x20000
	v_add_co_u32_e32 v68, vcc, s5, v116
	v_lshl_add_u64 v[72:73], v[116:117], 0, s[12:13]
	s_mov_b64 s[12:13], 0x30080
	v_lshl_add_u64 v[20:21], v[116:117], 0, s[10:11]
	v_lshl_add_u64 v[46:47], v[116:117], 0, s[8:9]
	v_addc_co_u32_e32 v69, vcc, 0, v117, vcc
	v_lshl_add_u64 v[74:75], v[116:117], 0, s[12:13]
	s_mov_b64 s[12:13], 0x80000
	s_mov_b32 s5, 0x80000
	global_load_dwordx4 v[4:7], v[116:117], off offset:16
	global_load_dwordx4 v[8:11], v[116:117], off
	global_load_dwordx4 v[12:15], v[44:45], off
	global_load_dwordx4 v[16:19], v[20:21], off offset:16
	s_nop 0
	global_load_dwordx4 v[20:23], v[68:69], off
	global_load_dwordx4 v[24:27], v[36:37], off offset:16
	global_load_dwordx4 v[28:31], v[116:117], off offset:144
	global_load_dwordx4 v[32:35], v[116:117], off offset:128
	s_nop 0
	global_load_dwordx4 v[36:39], v[46:47], off offset:16
	global_load_dwordx4 v[40:43], v[44:45], off offset:128
	s_nop 0
	global_load_dwordx4 v[44:47], v[52:53], off
	global_load_dwordx4 v[48:51], v[52:53], off offset:128
	s_nop 0
	global_load_dwordx4 v[52:55], v[70:71], off offset:16
	global_load_dwordx4 v[56:59], v[68:69], off offset:128
	global_load_dwordx4 v[60:63], v[72:73], off offset:16
	global_load_dwordx4 v[64:67], v[74:75], off offset:16
	v_lshl_add_u64 v[72:73], v[116:117], 0, s[12:13]
	v_add_co_u32_e32 v88, vcc, s5, v116
	s_mov_b64 s[12:13], 0x90000
	s_nop 0
	v_addc_co_u32_e32 v89, vcc, 0, v117, vcc
	v_lshl_add_u64 v[84:85], v[116:117], 0, s[12:13]
	s_mov_b32 s5, 0x90000
	s_mov_b64 s[12:13], 0xa0000
	v_add_co_u32_e32 v96, vcc, s5, v116
	v_lshl_add_u64 v[80:81], v[116:117], 0, s[12:13]
	s_mov_b64 s[12:13], 0xb0000
	v_addc_co_u32_e32 v97, vcc, 0, v117, vcc
	s_mov_b32 s5, 0xa0000
	v_lshl_add_u64 v[108:109], v[116:117], 0, s[12:13]
	s_mov_b64 s[12:13], 0x80080
	v_add_co_u32_e32 v112, vcc, s5, v116
	v_lshl_add_u64 v[100:101], v[116:117], 0, s[12:13]
	s_mov_b64 s[12:13], 0x90080
	v_addc_co_u32_e32 v113, vcc, 0, v117, vcc
	s_mov_b32 s5, 0xb0000
	v_lshl_add_u64 v[104:105], v[116:117], 0, s[12:13]
	s_mov_b64 s[12:13], 0xa0080
	v_add_co_u32_e32 v120, vcc, s5, v116
	v_lshl_add_u64 v[124:125], v[116:117], 0, s[12:13]
	s_mov_b64 s[12:13], 0xb0080
	v_addc_co_u32_e32 v121, vcc, 0, v117, vcc
	v_lshl_add_u64 v[128:129], v[116:117], 0, s[12:13]
	global_load_dwordx4 v[68:71], v[88:89], off
	s_nop 0
	global_load_dwordx4 v[72:75], v[72:73], off offset:16
	s_nop 0
	global_load_dwordx4 v[76:79], v[112:113], off
	s_nop 0
	global_load_dwordx4 v[80:83], v[80:81], off offset:16
	s_nop 0
	global_load_dwordx4 v[84:87], v[84:85], off offset:16
	s_nop 0
	global_load_dwordx4 v[88:91], v[88:89], off offset:128
	s_nop 0
	global_load_dwordx4 v[92:95], v[96:97], off
	s_nop 0
	global_load_dwordx4 v[96:99], v[96:97], off offset:128
	s_nop 0
	global_load_dwordx4 v[100:103], v[100:101], off offset:16
	s_nop 0
	global_load_dwordx4 v[104:107], v[104:105], off offset:16
	s_nop 0
	global_load_dwordx4 v[108:111], v[108:109], off offset:16
	s_nop 0
	global_load_dwordx4 v[112:115], v[112:113], off offset:128
	s_nop 0
	global_load_dwordx4 v[116:119], v[120:121], off
	s_nop 0
	global_load_dwordx4 v[120:123], v[120:121], off offset:128
	s_nop 0
	global_load_dwordx4 v[124:127], v[124:125], off offset:16
	s_nop 0
	global_load_dwordx4 v[128:131], v[128:129], off offset:16
	s_lshr_b32 s5, s39, 6
.Lp4x_done_w0:
	s_lshl_b32 s34, s5, 10
	s_ashr_i32 s5, s4, 31
	s_ashr_i32 s17, s16, 31
	s_lshl_b32 s12, s3, 6
	s_lshl_b64 s[14:15], s[4:5], 19
	s_lshl_b64 s[18:19], s[16:17], 19
	v_readlane_b32 s20, v254, 5
	v_readlane_b32 s21, v254, 6
	s_add_u32 s26, s20, s18
	s_addc_u32 s27, s21, s19
	s_add_i32 s5, s34, 0x100
	s_waitcnt lgkmcnt(0)
	v_lshl_add_u64 v[132:133], s[26:27], 0, v[158:159]
	s_add_i32 m0, s5, 0x10000
	s_mov_b64 s[18:19], 0x40000
	s_barrier
	global_load_lds_dwordx4 v158, s[26:27]
	v_lshl_add_u64 v[134:135], v[132:133], 0, s[18:19]
	s_add_i32 m0, s5, 0x12000
	s_mov_b64 s[20:21], 0x50000
	global_load_lds_dwordx4 v[134:135], off
	v_lshl_add_u64 v[134:135], v[132:133], 0, s[10:11]
	s_add_i32 m0, s5, 0x14000
	v_mov_b32_e32 v1, v159
	global_load_lds_dwordx4 v[134:135], off
	s_add_i32 m0, s5, 0x16000
	s_add_u32 s28, s40, s14
	v_lshl_add_u64 v[134:135], v[132:133], 0, s[20:21]
	s_addc_u32 s29, s41, s15
	global_load_lds_dwordx4 v[134:135], off
	v_lshl_add_u64 v[134:135], s[28:29], 0, v[0:1]
	s_mov_b32 m0, s5
	s_add_i32 s17, s5, 0x2000
	global_load_lds_dwordx4 v0, s[28:29]
	v_lshl_add_u64 v[136:137], v[134:135], 0, s[8:9]
	s_mov_b32 m0, s17
	s_add_i32 s35, s5, 0x4000
	global_load_lds_dwordx4 v[136:137], off
	v_lshl_add_u64 v[136:137], v[134:135], 0, s[18:19]
	s_mov_b32 m0, s35
	s_mov_b64 s[22:23], 0x60000
	s_add_i32 s38, s5, 0x6000
	global_load_lds_dwordx4 v[136:137], off
	v_lshl_add_u64 v[134:135], v[134:135], 0, s[22:23]
	s_mov_b32 m0, s38
	s_cmp_eq_u32 s44, 1
	global_load_lds_dwordx4 v[134:135], off
	s_cselect_b64 s[24:25], -1, 0
	s_cmp_lg_u32 s44, 1
	s_mov_b32 s13, 0x14000
	s_cbranch_scc1 .LBB0_964
	s_barrier
